# FF1 layer-1 GEMM epilogue rewritten (v_permlane16_swap exchange instead of ds_bpermute+cndmask, fewer VALU) + previous
# speedup vs baseline: 1.0041x; 1.0041x over previous
.LBB0_2906:
	s_or_b64 exec, exec, s[44:45]
	s_lshl_b32 s4, s61, 8
	v_lshrrev_b32_e32 v130, 4, v165
	v_lshlrev_b32_e32 v131, 2, v130
	v_bfe_u32 v132, v165, 4, 1
	v_mul_u32_u24_e32 v132, 12, v132
	v_add_u32_e32 v131, v131, v132
	v_lshlrev_b32_e32 v133, 5, v154
	v_or3_b32 v131, v133, s4, v131
	v_lshlrev_b32_e32 v134, 1, v131
	v_mov_b32_e32 v135, 0
	v_or_b32_e32 v136, s36, v156
	v_add_u32_e32 v136, v136, v157
	v_ashrrev_i32_e32 v137, 31, v136
	v_lshlrev_b64 v[136:137], 13, v[136:137]
	v_lshl_add_u64 v[134:135], s[8:9], 0, v[134:135]
	v_lshl_add_u64 v[134:135], v[134:135], 0, v[136:137]
	v_max_f32_e32 v124, 0, v124
	v_max_f32_e32 v125, 0, v125
	v_max_f32_e32 v126, 0, v126
	v_max_f32_e32 v127, 0, v127
	v_pk_mul_f32 v[124:125], v[124:125], v[124:125]
	v_pk_mul_f32 v[126:127], v[126:127], v[126:127]
	v_cvt_pk_bf16_f32 v200, v124, v125
	v_cvt_pk_bf16_f32 v201, v126, v127
	v_max_f32_e32 v120, 0, v120
	v_max_f32_e32 v121, 0, v121
	v_max_f32_e32 v122, 0, v122
	v_max_f32_e32 v123, 0, v123
	v_pk_mul_f32 v[120:121], v[120:121], v[120:121]
	v_pk_mul_f32 v[122:123], v[122:123], v[122:123]
	v_cvt_pk_bf16_f32 v202, v120, v121
	v_cvt_pk_bf16_f32 v203, v122, v123
	s_nop 0
	v_max_f32_e32 v92, 0, v92
	v_max_f32_e32 v93, 0, v93
	v_max_f32_e32 v94, 0, v94
	v_max_f32_e32 v95, 0, v95
	v_pk_mul_f32 v[92:93], v[92:93], v[92:93]
	v_pk_mul_f32 v[94:95], v[94:95], v[94:95]
	v_cvt_pk_bf16_f32 v204, v92, v93
	v_cvt_pk_bf16_f32 v205, v94, v95
	v_max_f32_e32 v88, 0, v88
	v_max_f32_e32 v89, 0, v89
	v_max_f32_e32 v90, 0, v90
	v_max_f32_e32 v91, 0, v91
	v_pk_mul_f32 v[88:89], v[88:89], v[88:89]
	v_pk_mul_f32 v[90:91], v[90:91], v[90:91]
	v_cvt_pk_bf16_f32 v206, v88, v89
	v_cvt_pk_bf16_f32 v207, v90, v91
	v_permlane16_swap_b32_e32 v200, v202
	v_permlane16_swap_b32_e32 v201, v203
	global_store_dwordx4 v[134:135], v[200:203], off
	v_max_f32_e32 v116, 0, v116
	v_max_f32_e32 v117, 0, v117
	v_max_f32_e32 v118, 0, v118
	v_max_f32_e32 v119, 0, v119
	v_pk_mul_f32 v[116:117], v[116:117], v[116:117]
	v_pk_mul_f32 v[118:119], v[118:119], v[118:119]
	v_cvt_pk_bf16_f32 v200, v116, v117
	v_cvt_pk_bf16_f32 v201, v118, v119
	v_max_f32_e32 v112, 0, v112
	v_max_f32_e32 v113, 0, v113
	v_max_f32_e32 v114, 0, v114
	v_max_f32_e32 v115, 0, v115
	v_pk_mul_f32 v[112:113], v[112:113], v[112:113]
	v_pk_mul_f32 v[114:115], v[114:115], v[114:115]
	v_cvt_pk_bf16_f32 v202, v112, v113
	v_cvt_pk_bf16_f32 v203, v114, v115
	v_permlane16_swap_b32_e32 v204, v206
	v_permlane16_swap_b32_e32 v205, v207
	global_store_dwordx4 v[134:135], v[204:207], off offset:256
	v_add_co_u32_e32 v134, vcc, 0x20000, v134
	s_nop 1
	v_addc_co_u32_e32 v135, vcc, 0, v135, vcc
	v_max_f32_e32 v84, 0, v84
	v_max_f32_e32 v85, 0, v85
	v_max_f32_e32 v86, 0, v86
	v_max_f32_e32 v87, 0, v87
	v_pk_mul_f32 v[84:85], v[84:85], v[84:85]
	v_pk_mul_f32 v[86:87], v[86:87], v[86:87]
	v_cvt_pk_bf16_f32 v204, v84, v85
	v_cvt_pk_bf16_f32 v205, v86, v87
	v_max_f32_e32 v80, 0, v80
	v_max_f32_e32 v81, 0, v81
	v_max_f32_e32 v82, 0, v82
	v_max_f32_e32 v83, 0, v83
	v_pk_mul_f32 v[80:81], v[80:81], v[80:81]
	v_pk_mul_f32 v[82:83], v[82:83], v[82:83]
	v_cvt_pk_bf16_f32 v206, v80, v81
	v_cvt_pk_bf16_f32 v207, v82, v83
	v_permlane16_swap_b32_e32 v200, v202
	v_permlane16_swap_b32_e32 v201, v203
	global_store_dwordx4 v[134:135], v[200:203], off
	v_max_f32_e32 v108, 0, v108
	v_max_f32_e32 v109, 0, v109
	v_max_f32_e32 v110, 0, v110
	v_max_f32_e32 v111, 0, v111
	v_pk_mul_f32 v[108:109], v[108:109], v[108:109]
	v_pk_mul_f32 v[110:111], v[110:111], v[110:111]
	v_cvt_pk_bf16_f32 v200, v108, v109
	v_cvt_pk_bf16_f32 v201, v110, v111
	v_max_f32_e32 v104, 0, v104
	v_max_f32_e32 v105, 0, v105
	v_max_f32_e32 v106, 0, v106
	v_max_f32_e32 v107, 0, v107
	v_pk_mul_f32 v[104:105], v[104:105], v[104:105]
	v_pk_mul_f32 v[106:107], v[106:107], v[106:107]
	v_cvt_pk_bf16_f32 v202, v104, v105
	v_cvt_pk_bf16_f32 v203, v106, v107
	v_permlane16_swap_b32_e32 v204, v206
	v_permlane16_swap_b32_e32 v205, v207
	global_store_dwordx4 v[134:135], v[204:207], off offset:256
	v_add_co_u32_e32 v134, vcc, 0x20000, v134
	s_nop 1
	v_addc_co_u32_e32 v135, vcc, 0, v135, vcc
	v_max_f32_e32 v76, 0, v76
	v_max_f32_e32 v77, 0, v77
	v_max_f32_e32 v78, 0, v78
	v_max_f32_e32 v79, 0, v79
	v_pk_mul_f32 v[76:77], v[76:77], v[76:77]
	v_pk_mul_f32 v[78:79], v[78:79], v[78:79]
	v_cvt_pk_bf16_f32 v204, v76, v77
	v_cvt_pk_bf16_f32 v205, v78, v79
	v_max_f32_e32 v72, 0, v72
	v_max_f32_e32 v73, 0, v73
	v_max_f32_e32 v74, 0, v74
	v_max_f32_e32 v75, 0, v75
	v_pk_mul_f32 v[72:73], v[72:73], v[72:73]
	v_pk_mul_f32 v[74:75], v[74:75], v[74:75]
	v_cvt_pk_bf16_f32 v206, v72, v73
	v_cvt_pk_bf16_f32 v207, v74, v75
	v_permlane16_swap_b32_e32 v200, v202
	v_permlane16_swap_b32_e32 v201, v203
	global_store_dwordx4 v[134:135], v[200:203], off
	v_max_f32_e32 v100, 0, v100
	v_max_f32_e32 v101, 0, v101
	v_max_f32_e32 v102, 0, v102
	v_max_f32_e32 v103, 0, v103
	v_pk_mul_f32 v[100:101], v[100:101], v[100:101]
	v_pk_mul_f32 v[102:103], v[102:103], v[102:103]
	v_cvt_pk_bf16_f32 v200, v100, v101
	v_cvt_pk_bf16_f32 v201, v102, v103
	v_max_f32_e32 v96, 0, v96
	v_max_f32_e32 v97, 0, v97
	v_max_f32_e32 v98, 0, v98
	v_max_f32_e32 v99, 0, v99
	v_pk_mul_f32 v[96:97], v[96:97], v[96:97]
	v_pk_mul_f32 v[98:99], v[98:99], v[98:99]
	v_cvt_pk_bf16_f32 v202, v96, v97
	v_cvt_pk_bf16_f32 v203, v98, v99
	v_permlane16_swap_b32_e32 v204, v206
	v_permlane16_swap_b32_e32 v205, v207
	global_store_dwordx4 v[134:135], v[204:207], off offset:256
	v_add_co_u32_e32 v134, vcc, 0x20000, v134
	s_nop 1
	v_addc_co_u32_e32 v135, vcc, 0, v135, vcc
	v_max_f32_e32 v68, 0, v68
	v_max_f32_e32 v69, 0, v69
	v_max_f32_e32 v70, 0, v70
	v_max_f32_e32 v71, 0, v71
	v_pk_mul_f32 v[68:69], v[68:69], v[68:69]
	v_pk_mul_f32 v[70:71], v[70:71], v[70:71]
	v_cvt_pk_bf16_f32 v204, v68, v69
	v_cvt_pk_bf16_f32 v205, v70, v71
	v_max_f32_e32 v64, 0, v64
	v_max_f32_e32 v65, 0, v65
	v_max_f32_e32 v66, 0, v66
	v_max_f32_e32 v67, 0, v67
	v_pk_mul_f32 v[64:65], v[64:65], v[64:65]
	v_pk_mul_f32 v[66:67], v[66:67], v[66:67]
	v_cvt_pk_bf16_f32 v206, v64, v65
	v_cvt_pk_bf16_f32 v207, v66, v67
	v_permlane16_swap_b32_e32 v200, v202
	v_permlane16_swap_b32_e32 v201, v203
	global_store_dwordx4 v[134:135], v[200:203], off
	v_max_f32_e32 v60, 0, v60
	v_max_f32_e32 v61, 0, v61
	v_max_f32_e32 v62, 0, v62
	v_max_f32_e32 v63, 0, v63
	v_pk_mul_f32 v[60:61], v[60:61], v[60:61]
	v_pk_mul_f32 v[62:63], v[62:63], v[62:63]
	v_cvt_pk_bf16_f32 v200, v60, v61
	v_cvt_pk_bf16_f32 v201, v62, v63
	v_max_f32_e32 v56, 0, v56
	v_max_f32_e32 v57, 0, v57
	v_max_f32_e32 v58, 0, v58
	v_max_f32_e32 v59, 0, v59
	v_pk_mul_f32 v[56:57], v[56:57], v[56:57]
	v_pk_mul_f32 v[58:59], v[58:59], v[58:59]
	v_cvt_pk_bf16_f32 v202, v56, v57
	v_cvt_pk_bf16_f32 v203, v58, v59
	v_permlane16_swap_b32_e32 v204, v206
	v_permlane16_swap_b32_e32 v205, v207
	global_store_dwordx4 v[134:135], v[204:207], off offset:256
	v_add_co_u32_e32 v134, vcc, 0xa0000, v134
	s_nop 1
	v_addc_co_u32_e32 v135, vcc, 0, v135, vcc
	v_max_f32_e32 v28, 0, v28
	v_max_f32_e32 v29, 0, v29
	v_max_f32_e32 v30, 0, v30
	v_max_f32_e32 v31, 0, v31
	v_pk_mul_f32 v[28:29], v[28:29], v[28:29]
	v_pk_mul_f32 v[30:31], v[30:31], v[30:31]
	v_cvt_pk_bf16_f32 v204, v28, v29
	v_cvt_pk_bf16_f32 v205, v30, v31
	v_max_f32_e32 v24, 0, v24
	v_max_f32_e32 v25, 0, v25
	v_max_f32_e32 v26, 0, v26
	v_max_f32_e32 v27, 0, v27
	v_pk_mul_f32 v[24:25], v[24:25], v[24:25]
	v_pk_mul_f32 v[26:27], v[26:27], v[26:27]
	v_cvt_pk_bf16_f32 v206, v24, v25
	v_cvt_pk_bf16_f32 v207, v26, v27
	v_permlane16_swap_b32_e32 v200, v202
	v_permlane16_swap_b32_e32 v201, v203
	global_store_dwordx4 v[134:135], v[200:203], off
	v_max_f32_e32 v52, 0, v52
	v_max_f32_e32 v53, 0, v53
	v_max_f32_e32 v54, 0, v54
	v_max_f32_e32 v55, 0, v55
	v_pk_mul_f32 v[52:53], v[52:53], v[52:53]
	v_pk_mul_f32 v[54:55], v[54:55], v[54:55]
	v_cvt_pk_bf16_f32 v200, v52, v53
	v_cvt_pk_bf16_f32 v201, v54, v55
	v_max_f32_e32 v48, 0, v48
	v_max_f32_e32 v49, 0, v49
	v_max_f32_e32 v50, 0, v50
	v_max_f32_e32 v51, 0, v51
	v_pk_mul_f32 v[48:49], v[48:49], v[48:49]
	v_pk_mul_f32 v[50:51], v[50:51], v[50:51]
	v_cvt_pk_bf16_f32 v202, v48, v49
	v_cvt_pk_bf16_f32 v203, v50, v51
	v_permlane16_swap_b32_e32 v204, v206
	v_permlane16_swap_b32_e32 v205, v207
	global_store_dwordx4 v[134:135], v[204:207], off offset:256
	v_add_co_u32_e32 v134, vcc, 0x20000, v134
	s_nop 1
	v_addc_co_u32_e32 v135, vcc, 0, v135, vcc
	v_max_f32_e32 v20, 0, v20
	v_max_f32_e32 v21, 0, v21
	v_max_f32_e32 v22, 0, v22
	v_max_f32_e32 v23, 0, v23
	v_pk_mul_f32 v[20:21], v[20:21], v[20:21]
	v_pk_mul_f32 v[22:23], v[22:23], v[22:23]
	v_cvt_pk_bf16_f32 v204, v20, v21
	v_cvt_pk_bf16_f32 v205, v22, v23
	v_max_f32_e32 v16, 0, v16
	v_max_f32_e32 v17, 0, v17
	v_max_f32_e32 v18, 0, v18
	v_max_f32_e32 v19, 0, v19
	v_pk_mul_f32 v[16:17], v[16:17], v[16:17]
	v_pk_mul_f32 v[18:19], v[18:19], v[18:19]
	v_cvt_pk_bf16_f32 v206, v16, v17
	v_cvt_pk_bf16_f32 v207, v18, v19
	v_permlane16_swap_b32_e32 v200, v202
	v_permlane16_swap_b32_e32 v201, v203
	global_store_dwordx4 v[134:135], v[200:203], off
	v_max_f32_e32 v44, 0, v44
	v_max_f32_e32 v45, 0, v45
	v_max_f32_e32 v46, 0, v46
	v_max_f32_e32 v47, 0, v47
	v_pk_mul_f32 v[44:45], v[44:45], v[44:45]
	v_pk_mul_f32 v[46:47], v[46:47], v[46:47]
	v_cvt_pk_bf16_f32 v200, v44, v45
	v_cvt_pk_bf16_f32 v201, v46, v47
	v_max_f32_e32 v40, 0, v40
	v_max_f32_e32 v41, 0, v41
	v_max_f32_e32 v42, 0, v42
	v_max_f32_e32 v43, 0, v43
	v_pk_mul_f32 v[40:41], v[40:41], v[40:41]
	v_pk_mul_f32 v[42:43], v[42:43], v[42:43]
	v_cvt_pk_bf16_f32 v202, v40, v41
	v_cvt_pk_bf16_f32 v203, v42, v43
	v_permlane16_swap_b32_e32 v204, v206
	v_permlane16_swap_b32_e32 v205, v207
	global_store_dwordx4 v[134:135], v[204:207], off offset:256
	v_add_co_u32_e32 v134, vcc, 0x20000, v134
	s_nop 1
	v_addc_co_u32_e32 v135, vcc, 0, v135, vcc
	v_max_f32_e32 v12, 0, v12
	v_max_f32_e32 v13, 0, v13
	v_max_f32_e32 v14, 0, v14
	v_max_f32_e32 v15, 0, v15
	v_pk_mul_f32 v[12:13], v[12:13], v[12:13]
	v_pk_mul_f32 v[14:15], v[14:15], v[14:15]
	v_cvt_pk_bf16_f32 v204, v12, v13
	v_cvt_pk_bf16_f32 v205, v14, v15
	v_max_f32_e32 v8, 0, v8
	v_max_f32_e32 v9, 0, v9
	v_max_f32_e32 v10, 0, v10
	v_max_f32_e32 v11, 0, v11
	v_pk_mul_f32 v[8:9], v[8:9], v[8:9]
	v_pk_mul_f32 v[10:11], v[10:11], v[10:11]
	v_cvt_pk_bf16_f32 v206, v8, v9
	v_cvt_pk_bf16_f32 v207, v10, v11
	v_permlane16_swap_b32_e32 v200, v202
	v_permlane16_swap_b32_e32 v201, v203
	global_store_dwordx4 v[134:135], v[200:203], off
	v_max_f32_e32 v36, 0, v36
	v_max_f32_e32 v37, 0, v37
	v_max_f32_e32 v38, 0, v38
	v_max_f32_e32 v39, 0, v39
	v_pk_mul_f32 v[36:37], v[36:37], v[36:37]
	v_pk_mul_f32 v[38:39], v[38:39], v[38:39]
	v_cvt_pk_bf16_f32 v200, v36, v37
	v_cvt_pk_bf16_f32 v201, v38, v39
	v_max_f32_e32 v32, 0, v32
	v_max_f32_e32 v33, 0, v33
	v_max_f32_e32 v34, 0, v34
	v_max_f32_e32 v35, 0, v35
	v_pk_mul_f32 v[32:33], v[32:33], v[32:33]
	v_pk_mul_f32 v[34:35], v[34:35], v[34:35]
	v_cvt_pk_bf16_f32 v202, v32, v33
	v_cvt_pk_bf16_f32 v203, v34, v35
	v_permlane16_swap_b32_e32 v204, v206
	v_permlane16_swap_b32_e32 v205, v207
	global_store_dwordx4 v[134:135], v[204:207], off offset:256
	v_add_co_u32_e32 v134, vcc, 0x20000, v134
	s_nop 1
	v_addc_co_u32_e32 v135, vcc, 0, v135, vcc
	v_max_f32_e32 v4, 0, v4
	v_max_f32_e32 v5, 0, v5
	v_max_f32_e32 v6, 0, v6
	v_max_f32_e32 v7, 0, v7
	v_pk_mul_f32 v[4:5], v[4:5], v[4:5]
	v_pk_mul_f32 v[6:7], v[6:7], v[6:7]
	v_cvt_pk_bf16_f32 v204, v4, v5
	v_cvt_pk_bf16_f32 v205, v6, v7
	v_max_f32_e32 v0, 0, v0
	v_max_f32_e32 v1, 0, v1
	v_max_f32_e32 v2, 0, v2
	v_max_f32_e32 v3, 0, v3
	v_pk_mul_f32 v[0:1], v[0:1], v[0:1]
	v_pk_mul_f32 v[2:3], v[2:3], v[2:3]
	v_cvt_pk_bf16_f32 v206, v0, v1
	v_cvt_pk_bf16_f32 v207, v2, v3
	v_permlane16_swap_b32_e32 v200, v202
	v_permlane16_swap_b32_e32 v201, v203
	global_store_dwordx4 v[134:135], v[200:203], off
	s_nop 1
	v_permlane16_swap_b32_e32 v204, v206
	v_permlane16_swap_b32_e32 v205, v207
	global_store_dwordx4 v[134:135], v[204:207], off offset:256
	s_lshr_b32 s2, s90, 3
	s_andn2_b64 vcc, exec, s[38:39]
	s_add_i32 s0, s0, s2
	s_waitcnt vmcnt(0)
	s_barrier
	s_cbranch_vccz .LBB0_2921
